# context-row GEMM K-loop: operand fragments of two k-slices loaded together into two register slots with counted waits instead of one load per vmcnt(0)
# speedup vs baseline: 1.0113x; 1.0042x over previous
.LBB0_1107:
	v_lshl_add_u64 v[100:101], v[84:85], 0, s[36:37]
	v_lshl_add_u64 v[98:99], v[80:81], 0, s[36:37]
	v_lshl_add_u64 v[94:95], v[76:77], 0, s[36:37]
	v_lshl_add_u64 v[92:93], v[72:73], 0, s[36:37]
	v_lshl_add_u64 v[96:97], v[70:71], 0, s[36:37]
	v_lshl_add_u64 v[88:89], v[74:75], 0, s[36:37]
	v_lshl_add_u64 v[90:91], v[78:79], 0, s[36:37]
	v_lshl_add_u64 v[86:87], v[82:83], 0, s[36:37]
	global_load_dwordx4 v[178:181], v[100:101], off
	global_load_dwordx4 v[182:185], v[98:99], off
	global_load_dwordx4 v[186:189], v[94:95], off
	global_load_dwordx4 v[190:193], v[92:93], off
	global_load_dwordx4 v[194:197], v[96:97], off
	global_load_dwordx4 v[198:201], v[88:89], off
	global_load_dwordx4 v[202:205], v[90:91], off
	global_load_dwordx4 v[206:209], v[86:87], off
	global_load_dwordx4 v[210:213], v[100:101], off offset:64
	global_load_dwordx4 v[214:217], v[98:99], off offset:64
	global_load_dwordx4 v[218:221], v[94:95], off offset:64
	global_load_dwordx4 v[222:225], v[92:93], off offset:64
	global_load_dwordx4 v[142:145], v[96:97], off offset:64
	global_load_dwordx4 v[146:149], v[88:89], off offset:64
	global_load_dwordx4 v[166:169], v[90:91], off offset:64
	global_load_dwordx4 v[170:173], v[86:87], off offset:64
	s_addk_i32 s17, 0x80
	v_lshl_add_u64 v[70:71], v[70:71], 0, s[38:39]
	v_lshl_add_u64 v[72:73], v[72:73], 0, s[38:39]
	v_lshl_add_u64 v[74:75], v[74:75], 0, s[38:39]
	v_lshl_add_u64 v[76:77], v[76:77], 0, s[38:39]
	v_lshl_add_u64 v[78:79], v[78:79], 0, s[38:39]
	v_lshl_add_u64 v[80:81], v[80:81], 0, s[38:39]
	v_lshl_add_u64 v[82:83], v[82:83], 0, s[38:39]
	v_lshl_add_u64 v[84:85], v[84:85], 0, s[38:39]
	s_cmp_ge_i32 s17, s49
	s_waitcnt vmcnt(8)
	v_mfma_f32_16x16x32_bf16 v[0:3], v[178:181], v[194:197], v[0:3]
	v_mfma_f32_16x16x32_bf16 v[4:7], v[182:185], v[194:197], v[4:7]
	v_mfma_f32_16x16x32_bf16 v[8:11], v[186:189], v[194:197], v[8:11]
	v_mfma_f32_16x16x32_bf16 v[12:15], v[190:193], v[194:197], v[12:15]
	v_mfma_f32_16x16x32_bf16 v[16:19], v[178:181], v[198:201], v[16:19]
	v_mfma_f32_16x16x32_bf16 v[20:23], v[182:185], v[198:201], v[20:23]
	v_mfma_f32_16x16x32_bf16 v[24:27], v[186:189], v[198:201], v[24:27]
	v_mfma_f32_16x16x32_bf16 v[28:31], v[190:193], v[198:201], v[28:31]
	v_mfma_f32_16x16x32_bf16 v[32:35], v[178:181], v[202:205], v[32:35]
	v_mfma_f32_16x16x32_bf16 v[36:39], v[182:185], v[202:205], v[36:39]
	v_mfma_f32_16x16x32_bf16 v[40:43], v[186:189], v[202:205], v[40:43]
	v_mfma_f32_16x16x32_bf16 v[44:47], v[190:193], v[202:205], v[44:47]
	v_mfma_f32_16x16x32_bf16 v[48:51], v[178:181], v[206:209], v[48:51]
	v_mfma_f32_16x16x32_bf16 v[56:59], v[182:185], v[206:209], v[56:59]
	v_mfma_f32_16x16x32_bf16 v[60:63], v[186:189], v[206:209], v[60:63]
	v_mfma_f32_16x16x32_bf16 v[52:55], v[190:193], v[206:209], v[52:55]
	global_load_dwordx4 v[178:181], v[100:101], off offset:128
	global_load_dwordx4 v[182:185], v[98:99], off offset:128
	global_load_dwordx4 v[186:189], v[94:95], off offset:128
	global_load_dwordx4 v[190:193], v[92:93], off offset:128
	global_load_dwordx4 v[194:197], v[96:97], off offset:128
	global_load_dwordx4 v[198:201], v[88:89], off offset:128
	global_load_dwordx4 v[202:205], v[90:91], off offset:128
	global_load_dwordx4 v[206:209], v[86:87], off offset:128
	s_waitcnt vmcnt(8)
	v_mfma_f32_16x16x32_bf16 v[0:3], v[210:213], v[142:145], v[0:3]
	v_mfma_f32_16x16x32_bf16 v[4:7], v[214:217], v[142:145], v[4:7]
	v_mfma_f32_16x16x32_bf16 v[8:11], v[218:221], v[142:145], v[8:11]
	v_mfma_f32_16x16x32_bf16 v[12:15], v[222:225], v[142:145], v[12:15]
	v_mfma_f32_16x16x32_bf16 v[16:19], v[210:213], v[146:149], v[16:19]
	v_mfma_f32_16x16x32_bf16 v[20:23], v[214:217], v[146:149], v[20:23]
	v_mfma_f32_16x16x32_bf16 v[24:27], v[218:221], v[146:149], v[24:27]
	v_mfma_f32_16x16x32_bf16 v[28:31], v[222:225], v[146:149], v[28:31]
	v_mfma_f32_16x16x32_bf16 v[32:35], v[210:213], v[166:169], v[32:35]
	v_mfma_f32_16x16x32_bf16 v[36:39], v[214:217], v[166:169], v[36:39]
	v_mfma_f32_16x16x32_bf16 v[40:43], v[218:221], v[166:169], v[40:43]
	v_mfma_f32_16x16x32_bf16 v[44:47], v[222:225], v[166:169], v[44:47]
	v_mfma_f32_16x16x32_bf16 v[48:51], v[210:213], v[170:173], v[48:51]
	v_mfma_f32_16x16x32_bf16 v[56:59], v[214:217], v[170:173], v[56:59]
	v_mfma_f32_16x16x32_bf16 v[60:63], v[218:221], v[170:173], v[60:63]
	v_mfma_f32_16x16x32_bf16 v[52:55], v[222:225], v[170:173], v[52:55]
	global_load_dwordx4 v[210:213], v[100:101], off offset:192
	global_load_dwordx4 v[214:217], v[98:99], off offset:192
	global_load_dwordx4 v[218:221], v[94:95], off offset:192
	global_load_dwordx4 v[222:225], v[92:93], off offset:192
	global_load_dwordx4 v[142:145], v[96:97], off offset:192
	global_load_dwordx4 v[146:149], v[88:89], off offset:192
	global_load_dwordx4 v[166:169], v[90:91], off offset:192
	global_load_dwordx4 v[170:173], v[86:87], off offset:192
	s_waitcnt vmcnt(8)
	v_mfma_f32_16x16x32_bf16 v[0:3], v[178:181], v[194:197], v[0:3]
	v_mfma_f32_16x16x32_bf16 v[4:7], v[182:185], v[194:197], v[4:7]
	v_mfma_f32_16x16x32_bf16 v[8:11], v[186:189], v[194:197], v[8:11]
	v_mfma_f32_16x16x32_bf16 v[12:15], v[190:193], v[194:197], v[12:15]
	v_mfma_f32_16x16x32_bf16 v[16:19], v[178:181], v[198:201], v[16:19]
	v_mfma_f32_16x16x32_bf16 v[20:23], v[182:185], v[198:201], v[20:23]
	v_mfma_f32_16x16x32_bf16 v[24:27], v[186:189], v[198:201], v[24:27]
	v_mfma_f32_16x16x32_bf16 v[28:31], v[190:193], v[198:201], v[28:31]
	v_mfma_f32_16x16x32_bf16 v[32:35], v[178:181], v[202:205], v[32:35]
	v_mfma_f32_16x16x32_bf16 v[36:39], v[182:185], v[202:205], v[36:39]
	v_mfma_f32_16x16x32_bf16 v[40:43], v[186:189], v[202:205], v[40:43]
	v_mfma_f32_16x16x32_bf16 v[44:47], v[190:193], v[202:205], v[44:47]
	v_mfma_f32_16x16x32_bf16 v[48:51], v[178:181], v[206:209], v[48:51]
	v_mfma_f32_16x16x32_bf16 v[56:59], v[182:185], v[206:209], v[56:59]
	v_mfma_f32_16x16x32_bf16 v[60:63], v[186:189], v[206:209], v[60:63]
	v_mfma_f32_16x16x32_bf16 v[52:55], v[190:193], v[206:209], v[52:55]
	s_waitcnt vmcnt(0)
	v_mfma_f32_16x16x32_bf16 v[0:3], v[210:213], v[142:145], v[0:3]
	v_mfma_f32_16x16x32_bf16 v[4:7], v[214:217], v[142:145], v[4:7]
	v_mfma_f32_16x16x32_bf16 v[8:11], v[218:221], v[142:145], v[8:11]
	v_mfma_f32_16x16x32_bf16 v[12:15], v[222:225], v[142:145], v[12:15]
	v_mfma_f32_16x16x32_bf16 v[16:19], v[210:213], v[146:149], v[16:19]
	v_mfma_f32_16x16x32_bf16 v[20:23], v[214:217], v[146:149], v[20:23]
	v_mfma_f32_16x16x32_bf16 v[24:27], v[218:221], v[146:149], v[24:27]
	v_mfma_f32_16x16x32_bf16 v[28:31], v[222:225], v[146:149], v[28:31]
	v_mfma_f32_16x16x32_bf16 v[32:35], v[210:213], v[166:169], v[32:35]
	v_mfma_f32_16x16x32_bf16 v[36:39], v[214:217], v[166:169], v[36:39]
	v_mfma_f32_16x16x32_bf16 v[40:43], v[218:221], v[166:169], v[40:43]
	v_mfma_f32_16x16x32_bf16 v[44:47], v[222:225], v[166:169], v[44:47]
	v_mfma_f32_16x16x32_bf16 v[48:51], v[210:213], v[170:173], v[48:51]
	v_mfma_f32_16x16x32_bf16 v[56:59], v[214:217], v[170:173], v[56:59]
	v_mfma_f32_16x16x32_bf16 v[60:63], v[218:221], v[170:173], v[60:63]
	v_mfma_f32_16x16x32_bf16 v[52:55], v[222:225], v[170:173], v[52:55]
	s_cbranch_scc0 .LBB0_1107
	ds_write2st64_b32 v102, v0, v1 offset1:1
	ds_write2st64_b32 v102, v2, v3 offset0:2 offset1:3
	ds_write2st64_b32 v102, v4, v5 offset0:4 offset1:5
	ds_write2st64_b32 v102, v6, v7 offset0:6 offset1:7
	ds_write2st64_b32 v102, v8, v9 offset0:8 offset1:9
	ds_write2st64_b32 v102, v10, v11 offset0:10 offset1:11
	ds_write2st64_b32 v102, v12, v13 offset0:12 offset1:13
	ds_write2st64_b32 v102, v14, v15 offset0:14 offset1:15
	ds_write2st64_b32 v102, v16, v17 offset0:16 offset1:17
	ds_write2st64_b32 v102, v18, v19 offset0:18 offset1:19
	ds_write2st64_b32 v102, v20, v21 offset0:20 offset1:21
	ds_write2st64_b32 v102, v22, v23 offset0:22 offset1:23
	ds_write2st64_b32 v102, v24, v25 offset0:24 offset1:25
	ds_write2st64_b32 v102, v26, v27 offset0:26 offset1:27
	ds_write2st64_b32 v102, v28, v29 offset0:28 offset1:29
	ds_write2st64_b32 v102, v30, v31 offset0:30 offset1:31
	ds_write2st64_b32 v102, v32, v33 offset0:32 offset1:33
	ds_write2st64_b32 v102, v34, v35 offset0:34 offset1:35
	ds_write2st64_b32 v102, v36, v37 offset0:36 offset1:37
	ds_write2st64_b32 v102, v38, v39 offset0:38 offset1:39
	ds_write2st64_b32 v102, v40, v41 offset0:40 offset1:41
	ds_write2st64_b32 v102, v42, v43 offset0:42 offset1:43
	ds_write2st64_b32 v102, v44, v45 offset0:44 offset1:45
	ds_write2st64_b32 v102, v46, v47 offset0:46 offset1:47
	ds_write2st64_b32 v102, v48, v49 offset0:48 offset1:49
	ds_write2st64_b32 v102, v50, v51 offset0:50 offset1:51
	ds_write2st64_b32 v102, v56, v57 offset0:52 offset1:53
	ds_write2st64_b32 v102, v58, v59 offset0:54 offset1:55
	ds_write2st64_b32 v102, v60, v61 offset0:56 offset1:57
	ds_write2st64_b32 v102, v62, v63 offset0:58 offset1:59
	ds_write2st64_b32 v102, v52, v53 offset0:60 offset1:61
	ds_write2st64_b32 v102, v54, v55 offset0:62 offset1:63
	s_waitcnt lgkmcnt(0)
	s_barrier
	ds_read2st64_b32 v[0:1], v103 offset1:1
	ds_read2st64_b32 v[2:3], v103 offset0:4 offset1:5
	ds_read2st64_b32 v[6:7], v103 offset0:6 offset1:7
	ds_read2st64_b32 v[4:5], v103 offset0:2 offset1:3
	ds_read2st64_b32 v[8:9], v103 offset0:64 offset1:65
	ds_read2st64_b32 v[10:11], v103 offset0:68 offset1:69
	ds_read2st64_b32 v[12:13], v103 offset0:70 offset1:71
	ds_read2st64_b32 v[14:15], v103 offset0:66 offset1:67
	ds_read2st64_b32 v[16:17], v103 offset0:128 offset1:129
	ds_read2st64_b32 v[18:19], v103 offset0:132 offset1:133
	ds_read2st64_b32 v[20:21], v103 offset0:134 offset1:135
	ds_read2st64_b32 v[22:23], v103 offset0:130 offset1:131
	ds_read2st64_b32 v[24:25], v103 offset0:192 offset1:193
	ds_read2st64_b32 v[26:27], v103 offset0:196 offset1:197
	ds_read2st64_b32 v[28:29], v103 offset0:198 offset1:199
	ds_read2st64_b32 v[30:31], v103 offset0:194 offset1:195
	ds_read_b32 v32, v104
	ds_read_b32 v34, v105
	ds_read_b32 v33, v106
	ds_read_b32 v35, v107
	ds_read_b32 v36, v108
	ds_read_b32 v38, v109
	ds_read_b32 v37, v110
	ds_read_b32 v39, v111
	ds_read_b32 v40, v112
	ds_read_b32 v42, v113
	ds_read_b32 v41, v114
	ds_read_b32 v43, v115
	ds_read_b32 v44, v116
	ds_read_b32 v46, v117
	ds_read_b32 v45, v118
	ds_read_b32 v47, v119
	ds_read_b32 v48, v120
	ds_read_b32 v50, v121
	ds_read_b32 v49, v122
	ds_read_b32 v51, v123
	ds_read_b32 v52, v124
	ds_read_b32 v54, v125
	ds_read_b32 v53, v126
	ds_read_b32 v55, v127
	s_waitcnt lgkmcnt(14)
	v_pk_add_f32 v[0:1], v[0:1], 0 op_sel_hi:[1,0]
	v_pk_add_f32 v[2:3], v[2:3], 0 op_sel_hi:[1,0]
	v_pk_add_f32 v[0:1], v[0:1], v[8:9]
	v_pk_add_f32 v[4:5], v[4:5], 0 op_sel_hi:[1,0]
	v_pk_add_f32 v[0:1], v[0:1], v[16:17]
	v_pk_add_f32 v[6:7], v[6:7], 0 op_sel_hi:[1,0]
	v_pk_add_f32 v[0:1], v[0:1], v[24:25]
	v_pk_add_f32 v[2:3], v[2:3], v[10:11]
	v_pk_add_f32 v[4:5], v[4:5], v[14:15]
	v_pk_add_f32 v[6:7], v[6:7], v[12:13]
	v_pk_add_f32 v[0:1], v[0:1], v[32:33]
	ds_read_b32 v8, v128
	ds_read_b32 v16, v129
	ds_read_b32 v9, v130
	ds_read_b32 v17, v131
	ds_read_b32 v24, v132
	ds_read_b32 v32, v133
	ds_read_b32 v25, v134
	ds_read_b32 v33, v135
	v_pk_add_f32 v[2:3], v[2:3], v[18:19]
	v_pk_add_f32 v[4:5], v[4:5], v[22:23]
	v_pk_add_f32 v[6:7], v[6:7], v[20:21]
	v_pk_add_f32 v[2:3], v[2:3], v[26:27]
	v_pk_add_f32 v[4:5], v[4:5], v[30:31]
	v_pk_add_f32 v[6:7], v[6:7], v[28:29]
	s_lshl_b32 s55, s16, 6
	s_mul_i32 s16, s16, s44
	v_pk_add_f32 v[2:3], v[2:3], v[34:35]
	v_pk_add_f32 v[4:5], v[4:5], v[36:37]
	v_pk_add_f32 v[6:7], v[6:7], v[38:39]
	s_sub_i32 s53, s35, s16
	s_waitcnt lgkmcnt(14)
	v_pk_add_f32 v[0:1], v[0:1], v[40:41]
	v_pk_add_f32 v[2:3], v[2:3], v[42:43]
	v_pk_add_f32 v[4:5], v[4:5], v[44:45]
	v_pk_add_f32 v[6:7], v[6:7], v[46:47]
	s_lshl_b32 s56, s53, 6
	s_waitcnt lgkmcnt(13)
	v_pk_add_f32 v[0:1], v[0:1], v[48:49]
	s_waitcnt lgkmcnt(12)
	v_pk_add_f32 v[2:3], v[2:3], v[50:51]
	s_waitcnt lgkmcnt(9)
	v_pk_add_f32 v[4:5], v[4:5], v[52:53]
	s_waitcnt lgkmcnt(8)
	v_pk_add_f32 v[6:7], v[6:7], v[54:55]
	s_add_i32 s54, s51, s55
	s_waitcnt lgkmcnt(5)
	v_pk_add_f32 v[0:1], v[0:1], v[8:9]
	s_waitcnt lgkmcnt(4)
	v_pk_add_f32 v[2:3], v[2:3], v[16:17]
	s_waitcnt lgkmcnt(1)
	v_pk_add_f32 v[4:5], v[4:5], v[24:25]
	s_waitcnt lgkmcnt(0)
	v_pk_add_f32 v[6:7], v[6:7], v[32:33]
	v_or_b32_e32 v10, s54, v65
	v_or_b32_e32 v8, s56, v136
	s_mov_b64 s[40:41], -1
	s_mov_b64 s[38:39], 0
	s_cmp_lt_i32 s79, 22
	s_mov_b64 s[16:17], 0
	s_cbranch_scc1 .LBB0_1135
	s_cmp_gt_i32 s79, 23
	s_cbranch_scc0 .LBB0_1129
	s_cmp_gt_i32 s79, 24
	s_cbranch_scc0 .LBB0_1126
	s_cmp_gt_i32 s79, 25
	s_cbranch_scc0 .LBB0_1115
	s_cmp_eq_u32 s79, 26
	s_mov_b64 s[16:17], -1
	s_cbranch_scc0 .LBB0_1114
	v_max_f32_e32 v11, v2, v2
	v_max_f32_e32 v11, 0, v11
	v_max_f32_e32 v9, v0, v0
	v_mul_f32_e32 v16, v11, v11
	v_max_f32_e32 v11, v3, v3
	v_max_f32_e32 v9, 0, v9
	v_max_f32_e32 v11, 0, v11
	v_mul_f32_e32 v14, v9, v9
	v_max_f32_e32 v9, v1, v1
	v_mul_f32_e32 v17, v11, v11
	v_max_f32_e32 v11, v6, v6
	v_max_f32_e32 v9, 0, v9
	v_max_f32_e32 v11, 0, v11
	v_mul_f32_e32 v15, v9, v9
	v_max_f32_e32 v9, v4, v4
	v_mul_f32_e32 v19, v11, v11
	v_max_f32_e32 v11, v7, v7
	v_max_f32_e32 v9, 0, v9
	v_max_f32_e32 v11, 0, v11
	v_mul_f32_e32 v18, v9, v9
	v_max_f32_e32 v9, v5, v5
	v_mul_f32_e32 v21, v11, v11
	v_ashrrev_i32_e32 v11, 31, v10
	v_max_f32_e32 v9, 0, v9
	v_lshlrev_b64 v[12:13], 13, v[10:11]
	v_mul_f32_e32 v20, v9, v9
	v_lshl_add_u64 v[12:13], s[6:7], 0, v[12:13]
	v_ashrrev_i32_e32 v9, 31, v8
	v_lshl_add_u64 v[12:13], v[8:9], 1, v[12:13]
	v_cvt_pk_bf16_f32 v14, v14, v15
	v_cvt_pk_bf16_f32 v15, v18, v20
	global_store_dwordx2 v[12:13], v[14:15], off
	v_cvt_pk_bf16_f32 v14, v16, v17
	v_cvt_pk_bf16_f32 v15, v19, v21
	global_store_dwordx2 v[12:13], v[14:15], off offset:32
	s_mov_b64 s[16:17], 0
